# stack17 with K fragments prefetched four MFMAs ahead in the QK chain (5 reads upfront, 4 rotating buffers)
# speedup vs baseline: 1.0270x; 1.0023x over previous
.Li0_entry:
	v_add_u32_e32 v167, s79, v147
	v_add_u32_e32 v227, s79, v149
	v_add_u32_e32 v194, s79, v151
	v_add_u32_e32 v195, s79, v153
	ds_read_b128 v[64:67], v167
	ds_read_b128 v[188:191], v227
	ds_read_b128 v[228:231], v194
	ds_read_b128 v[184:187], v195
	ds_read_b128 v[180:183], v167 offset:128
	s_waitcnt lgkmcnt(4)
	v_mfma_f32_32x32x16_bf16 v[64:79], v[64:67], v[80:83], 0
	s_waitcnt lgkmcnt(3)
	v_mfma_f32_32x32x16_bf16 v[64:79], v[188:191], v[84:87], v[64:79]
	ds_read_b128 v[188:191], v227 offset:128
	s_mov_b64 s[54:55], 0xe404000
	s_add_i32 m0, s96, 0x8000
	v_lshl_add_u64 v[192:193], v[134:135], 0, s[54:55]
	s_nop 0
	global_load_lds_dwordx4 v[192:193], off
	v_cndmask_b32_e64 v173, v113, v121, s[2:3]
	v_cndmask_b32_e64 v172, v112, v120, s[2:3]
	v_cndmask_b32_e64 v177, v121, v113, s[2:3]
	v_cndmask_b32_e64 v176, v120, v112, s[2:3]
	s_waitcnt lgkmcnt(3)
	v_mfma_f32_32x32x16_bf16 v[64:79], v[228:231], v[88:91], v[64:79]
	ds_read_b128 v[228:231], v194 offset:128
	s_mov_b64 s[54:55], 0xe406000
	s_add_i32 m0, s96, 0xa000
	v_lshl_add_u64 v[192:193], v[134:135], 0, s[54:55]
	s_nop 0
	global_load_lds_dwordx4 v[192:193], off
	v_cndmask_b32_e64 v171, v119, v127, s[2:3]
	v_cndmask_b32_e64 v170, v118, v126, s[2:3]
	v_cndmask_b32_e64 v169, v117, v125, s[2:3]
	v_cndmask_b32_e64 v168, v116, v124, s[2:3]
	s_waitcnt lgkmcnt(3)
	v_mfma_f32_32x32x16_bf16 v[64:79], v[184:187], v[92:95], v[64:79]
	ds_read_b128 v[184:187], v195 offset:128
	s_mov_b64 s[54:55], 0xe804000
	s_add_i32 m0, s96, 0xc000
	v_lshl_add_u64 v[192:193], v[134:135], 0, s[54:55]
	s_nop 0
	global_load_lds_dwordx4 v[192:193], off
	v_cndmask_b32_e64 v175, v115, v123, s[2:3]
	v_cndmask_b32_e64 v174, v114, v122, s[2:3]
	v_cndmask_b32_e64 v127, v127, v119, s[2:3]
	v_cndmask_b32_e64 v126, v126, v118, s[2:3]
	s_waitcnt lgkmcnt(3)
	v_mfma_f32_32x32x16_bf16 v[64:79], v[180:183], v[96:99], v[64:79]
	ds_read_b64_tr_b16 v[180:181], v158 offset:0
	ds_read_b64_tr_b16 v[182:183], v158 offset:0x800
	s_mov_b64 s[54:55], 0xe806000
	s_add_i32 m0, s96, 0xe000
	v_lshl_add_u64 v[192:193], v[134:135], 0, s[54:55]
	s_nop 0
	global_load_lds_dwordx4 v[192:193], off
	v_cndmask_b32_e64 v125, v125, v117, s[2:3]
	v_cndmask_b32_e64 v124, v124, v116, s[2:3]
	v_cndmask_b32_e64 v179, v123, v115, s[2:3]
	v_cndmask_b32_e64 v178, v122, v114, s[2:3]
	s_waitcnt lgkmcnt(4)
	v_mfma_f32_32x32x16_bf16 v[64:79], v[188:191], v[100:103], v[64:79]
	s_cmp_gt_i32 s19, s18
	s_cbranch_scc1 .Li0_kskip
	v_lshl_add_u64 v[192:193], s[50:51], 0, v[130:131]
	s_mov_b64 s[54:55], 0xc408000
	s_mov_b32 m0, s97
	v_lshl_add_u64 v[192:193], v[192:193], 0, s[54:55]
	s_nop 0
	global_load_lds_dwordx4 v[192:193], off
	v_lshl_add_u64 v[192:193], s[50:51], 0, v[130:131]
	s_mov_b64 s[54:55], 0xc40a000
	s_mov_b32 m0, s26
	v_lshl_add_u64 v[192:193], v[192:193], 0, s[54:55]
	s_nop 0
	global_load_lds_dwordx4 v[192:193], off
.Li0_kskip:
	s_waitcnt lgkmcnt(3)
	v_mfma_f32_32x32x16_bf16 v[64:79], v[228:231], v[104:107], v[64:79]
	v_max_f32_e32 v194, v166, v166
	v_max_f32_e32 v195, v164, v164
	v_max_f32_e32 v194, v195, v194
	v_sub_f32_e32 v195, v194, v165
	v_mul_f32_e32 v195, 0x3db504f3, v195
	v_cmp_ge_f32_e32 vcc, s88, v195
	s_waitcnt lgkmcnt(2)
	v_mfma_f32_32x32x16_bf16 v[64:79], v[184:187], v[108:111], v[64:79]
	ds_read_b64_tr_b16 v[184:185], v158 offset:0x200
	ds_read_b64_tr_b16 v[186:187], v158 offset:0xa00
	s_cmp_eq_u64 vcc, exec
	s_cbranch_scc0 .Li0_fb
	v_mov_b32_e32 v166, v165
	s_sub_i32 s52, s83, 64
	s_cmp_le_i32 s52, s25
	s_cbranch_scc1 .Li0_sm
	s_nop 7
	v_add_u32_e32 v112, 0x5b, v162
	v_cmp_gt_u32_e32 vcc, s86, v112
	v_add_u32_e32 v112, s83, v163
	v_add_u32_e32 v112, 0xffffffa1, v112
	v_cndmask_b32_e32 v64, v141, v64, vcc
	v_cmp_lt_u32_e32 vcc, s87, v112
	v_add_u32_e32 v112, 0x59, v162
	s_nop 0
	v_cndmask_b32_e32 v65, v141, v65, vcc
	v_cmp_gt_u32_e32 vcc, s86, v112
	v_add_u32_e32 v112, 0x58, v162
	s_nop 0
	v_cndmask_b32_e32 v66, v141, v66, vcc
	v_cmp_gt_u32_e32 vcc, s86, v112
	v_add_u32_e32 v112, 0x53, v162
	s_nop 0
	v_cndmask_b32_e32 v67, v141, v67, vcc
	v_cmp_gt_u32_e32 vcc, s86, v112
	v_add_u32_e32 v112, 0x52, v162
	s_nop 0
	v_cndmask_b32_e32 v68, v141, v68, vcc
	v_cmp_gt_u32_e32 vcc, s86, v112
	v_add_u32_e32 v112, 0x51, v162
	s_nop 0
	v_cndmask_b32_e32 v69, v141, v69, vcc
	v_cmp_gt_u32_e32 vcc, s86, v112
	v_add_u32_e32 v112, 0x50, v162
	s_nop 0
	v_cndmask_b32_e32 v70, v141, v70, vcc
	v_cmp_gt_u32_e32 vcc, s86, v112
	v_add_u32_e32 v112, 0x4b, v162
	s_nop 0
	v_cndmask_b32_e32 v71, v141, v71, vcc
	v_cmp_gt_u32_e32 vcc, s86, v112
	v_add_u32_e32 v112, 0x4a, v162
	s_nop 0
	v_cndmask_b32_e32 v72, v141, v72, vcc
	v_cmp_gt_u32_e32 vcc, s86, v112
	v_add_u32_e32 v112, 0x49, v162
	s_nop 0
	v_cndmask_b32_e32 v73, v141, v73, vcc
	v_cmp_gt_u32_e32 vcc, s86, v112
	v_add_u32_e32 v112, 0x48, v162
	s_nop 0
	v_cndmask_b32_e32 v74, v141, v74, vcc
	v_cmp_gt_u32_e32 vcc, s86, v112
	v_add_u32_e32 v112, 0x43, v162
	s_nop 0
	v_cndmask_b32_e32 v75, v141, v75, vcc
	v_cmp_gt_u32_e32 vcc, s86, v112
	v_add_u32_e32 v112, 0x42, v162
	s_nop 0
	v_cndmask_b32_e32 v76, v141, v76, vcc
	v_cmp_gt_u32_e32 vcc, s86, v112
	v_add_u32_e32 v112, 0x41, v162
	s_nop 0
	v_cndmask_b32_e32 v77, v141, v77, vcc
	v_cmp_gt_u32_e32 vcc, s86, v112
	v_add_u32_e32 v112, 64, v162
	s_nop 0
	v_cndmask_b32_e32 v78, v141, v78, vcc
	v_cmp_gt_u32_e32 vcc, s86, v112
	s_nop 1
	v_cndmask_b32_e32 v79, v141, v79, vcc

.Li1_entry:
	ds_read_b128 v[64:67], v148
	ds_read_b128 v[188:191], v150
	ds_read_b128 v[228:231], v152
	ds_read_b128 v[184:187], v154
	ds_read_b128 v[180:183], v148 offset:128
	s_waitcnt lgkmcnt(4)
	v_mfma_f32_32x32x16_bf16 v[64:79], v[64:67], v[80:83], 0
	s_waitcnt lgkmcnt(3)
	v_mfma_f32_32x32x16_bf16 v[64:79], v[188:191], v[84:87], v[64:79]
	ds_read_b128 v[188:191], v150 offset:128
	s_mov_b64 s[56:57], 0xe408000
	s_mov_b32 m0, s96
	v_lshl_add_u64 v[192:193], v[134:135], 0, s[56:57]
	s_nop 0
	global_load_lds_dwordx4 v[192:193], off
	v_cndmask_b32_e64 v173, v113, v121, s[2:3]
	v_cndmask_b32_e64 v172, v112, v120, s[2:3]
	v_cndmask_b32_e64 v177, v121, v113, s[2:3]
	v_cndmask_b32_e64 v176, v120, v112, s[2:3]
	s_waitcnt lgkmcnt(3)
	v_mfma_f32_32x32x16_bf16 v[64:79], v[228:231], v[88:91], v[64:79]
	ds_read_b128 v[228:231], v152 offset:128
	s_mov_b64 s[56:57], 0xe40a000
	s_mov_b32 m0, s6
	v_lshl_add_u64 v[192:193], v[134:135], 0, s[56:57]
	s_nop 0
	global_load_lds_dwordx4 v[192:193], off
	v_cndmask_b32_e64 v171, v127, v119, s[2:3]
	v_cndmask_b32_e64 v170, v126, v118, s[2:3]
	v_cndmask_b32_e64 v169, v125, v117, s[2:3]
	v_cndmask_b32_e64 v168, v124, v116, s[2:3]
	s_waitcnt lgkmcnt(3)
	v_mfma_f32_32x32x16_bf16 v[64:79], v[184:187], v[92:95], v[64:79]
	ds_read_b128 v[184:187], v154 offset:128
	s_mov_b64 s[56:57], 0xe808000
	s_mov_b32 m0, s7
	v_lshl_add_u64 v[192:193], v[134:135], 0, s[56:57]
	s_nop 0
	global_load_lds_dwordx4 v[192:193], off
	v_cndmask_b32_e64 v175, v115, v123, s[2:3]
	v_cndmask_b32_e64 v174, v114, v122, s[2:3]
	v_cndmask_b32_e64 v127, v119, v127, s[2:3]
	v_cndmask_b32_e64 v126, v118, v126, s[2:3]
	s_waitcnt lgkmcnt(3)
	v_mfma_f32_32x32x16_bf16 v[64:79], v[180:183], v[96:99], v[64:79]
	ds_read_b64_tr_b16 v[180:181], v158 offset:0x8000
	ds_read_b64_tr_b16 v[182:183], v158 offset:0x8800
	s_mov_b64 s[56:57], 0xe80a000
	s_mov_b32 m0, s24
	v_lshl_add_u64 v[192:193], v[134:135], 0, s[56:57]
	s_nop 0
	global_load_lds_dwordx4 v[192:193], off
	v_cndmask_b32_e64 v125, v117, v125, s[2:3]
	v_cndmask_b32_e64 v124, v116, v124, s[2:3]
	v_cndmask_b32_e64 v179, v123, v115, s[2:3]
	v_cndmask_b32_e64 v178, v122, v114, s[2:3]
	s_waitcnt lgkmcnt(4)
	v_mfma_f32_32x32x16_bf16 v[64:79], v[188:191], v[100:103], v[64:79]
	s_add_i32 s56, s19, 1
	s_cmp_gt_i32 s56, s18
	s_cbranch_scc1 .Li1_kskip
	v_lshl_add_u64 v[192:193], s[50:51], 0, v[130:131]
	s_mov_b64 s[56:57], 0xc40c000
	s_mov_b32 m0, s27
	v_lshl_add_u64 v[192:193], v[192:193], 0, s[56:57]
	s_nop 0
	global_load_lds_dwordx4 v[192:193], off
	v_lshl_add_u64 v[192:193], s[50:51], 0, v[130:131]
	s_mov_b64 s[56:57], 0xc40e000
	s_mov_b32 m0, s62
	v_lshl_add_u64 v[192:193], v[192:193], 0, s[56:57]
	s_nop 0
	global_load_lds_dwordx4 v[192:193], off
.Li1_kskip:
	s_waitcnt lgkmcnt(3)
	v_mfma_f32_32x32x16_bf16 v[64:79], v[228:231], v[104:107], v[64:79]
	v_max_f32_e32 v194, v128, v128
	v_max_f32_e32 v195, v164, v164
	v_max_f32_e32 v194, v195, v194
	v_sub_f32_e32 v195, v194, v166
	v_mul_f32_e32 v195, 0x3db504f3, v195
	v_cmp_ge_f32_e32 vcc, s88, v195
	s_waitcnt lgkmcnt(2)
	v_mfma_f32_32x32x16_bf16 v[64:79], v[184:187], v[108:111], v[64:79]
	ds_read_b64_tr_b16 v[184:185], v158 offset:0x8200
	ds_read_b64_tr_b16 v[186:187], v158 offset:0x8a00
	s_cmp_eq_u64 vcc, exec
	s_cbranch_scc0 .Li1_fb
	v_mov_b32_e32 v165, v166
	s_cmp_le_i32 s83, s25
	s_cbranch_scc1 .Li1_sm
	s_nop 7
	v_add_u32_e32 v112, 27, v162
	v_cmp_gt_u32_e32 vcc, s86, v112
	v_add_u32_e32 v112, s83, v163
	v_subrev_u32_e32 v112, 31, v112
	v_cndmask_b32_e32 v64, v141, v64, vcc
	v_cmp_lt_u32_e32 vcc, s87, v112
	v_add_u32_e32 v112, 25, v162
	s_nop 0
	v_cndmask_b32_e32 v65, v141, v65, vcc
	v_cmp_gt_u32_e32 vcc, s86, v112
	v_add_u32_e32 v112, 24, v162
	s_nop 0
	v_cndmask_b32_e32 v66, v141, v66, vcc
	v_cmp_gt_u32_e32 vcc, s86, v112
	v_add_u32_e32 v112, 19, v162
	s_nop 0
	v_cndmask_b32_e32 v67, v141, v67, vcc
	v_cmp_gt_u32_e32 vcc, s86, v112
	v_add_u32_e32 v112, 18, v162
	s_nop 0
	v_cndmask_b32_e32 v68, v141, v68, vcc
	v_cmp_gt_u32_e32 vcc, s86, v112
	v_add_u32_e32 v112, 17, v162
	s_nop 0
	v_cndmask_b32_e32 v69, v141, v69, vcc
	v_cmp_gt_u32_e32 vcc, s86, v112
	v_add_u32_e32 v112, 16, v162
	s_nop 0
	v_cndmask_b32_e32 v70, v141, v70, vcc
	v_cmp_gt_u32_e32 vcc, s86, v112
	v_add_u32_e32 v112, 11, v162
	s_nop 0
	v_cndmask_b32_e32 v71, v141, v71, vcc
	v_cmp_gt_u32_e32 vcc, s86, v112
	v_add_u32_e32 v112, 10, v162
	s_nop 0
	v_cndmask_b32_e32 v72, v141, v72, vcc
	v_cmp_gt_u32_e32 vcc, s86, v112
	v_add_u32_e32 v112, 9, v162
	s_nop 0
	v_cndmask_b32_e32 v73, v141, v73, vcc
	v_cmp_gt_u32_e32 vcc, s86, v112
	v_add_u32_e32 v112, 8, v162
	s_nop 0
	v_cndmask_b32_e32 v74, v141, v74, vcc
	v_cmp_gt_u32_e32 vcc, s86, v112
	v_add_u32_e32 v112, 3, v162
	s_nop 0
	v_cndmask_b32_e32 v75, v141, v75, vcc
	v_cmp_gt_u32_e32 vcc, s86, v112
	v_add_u32_e32 v112, 2, v162
	s_nop 0
	v_cndmask_b32_e32 v76, v141, v76, vcc
	v_cmp_gt_u32_e32 vcc, s86, v112
	v_add_u32_e32 v112, 1, v162
	s_nop 0
	v_cndmask_b32_e32 v77, v141, v77, vcc
	v_cmp_gt_u32_e32 vcc, s86, v112
	s_nop 1
	v_cndmask_b32_e32 v78, v141, v78, vcc
	v_cmp_gt_u32_e32 vcc, s86, v162
	s_nop 1
	v_cndmask_b32_e32 v79, v141, v79, vcc
